# v44 with the in-proj A parked stores issued in K-loop iterations 4-7 instead of 0-3
# speedup vs baseline: 1.0088x; 1.0045x over previous
; #define PG8_STAGE(bufoff, gbase, voff) do { _Pragma("unroll") for (int _i = 0; _i < 2; ++_i) \
;         __builtin_amdgcn_global_load_lds((const unsigned*)((const char*)(gbase) + (voff)[_i]), (PG8_LAS unsigned*)(lds + (bufoff) + ldsw + _i * 8192), 16, 0, 0); } while (0)
; #define PG8_LDA(dst, b, h) do { _Pragma("unroll") for (int m = 0; m < 4; ++m) _Pragma("unroll") for (int k = 0; k < 2; ++k) dst[m][k] = *(const PG8_LAS bf16x8*)(lds + PG8_SA(b, h) + aoff + m * 2048 + k * 1024); } while (0)
; #define PG8_LDB(dst, b, h) do { _Pragma("unroll") for (int n = 0; n < 2; ++n) _Pragma("unroll") for (int k = 0; k < 2; ++k) dst[n][k] = *(const PG8_LAS bf16x8*)(lds + PG8_SB(b, h) + boff + n * 2048 + k * 1024); } while (0)
; #define PG8_SCHED __builtin_amdgcn_sched_barrier(0)
;     ...
;         const bool has_next = S.next(ui + 1, nxt);
;         const char* nA = has_next ? (const char*)g.A + (size_t)nxt.pm * tstep : cA; const char* nB = has_next ? (const char*)g.Bt + (size_t)nxt.pn * tstep : cB;
;         for (int t = 0; t < nt; t += 2) {
;             const bool last = (t == nt - 2);
;             const char* a1 = cA + (size_t)(t + 1) * kstep;
;             const char* a2 = last ? nA : cA + (size_t)(t + 2) * kstep; const char* b2 = last ? nB : cB + (size_t)(t + 2) * kstep;
;             const char* a3 = a2 + kstep; const char* b3 = b2 + kstep;
;             PG8_LDB(B0, 0, 0); PG8_LDB(B1, 0, 1); PG8_SCHED; PG8_LDA(At, 0, 0); PG8_STAGE(PG8_SA(1, 1), a1 + hstep, voffA);
.LBB0_206:
	s_add_u32 s72, s38, 0xfffc0080
	s_addc_u32 s73, s39, -1
	s_add_i32 s82, 0, 0x10000
	s_cmp_eq_u32 s81, 12
	s_cselect_b32 s77, s2, s73
	s_cselect_b32 s76, s31, s72
	s_cselect_b32 s73, s29, s80
	s_cselect_b32 s72, s60, s61
	s_add_i32 s86, 0, 0x14000
	s_waitcnt lgkmcnt(0)
	v_add_u32_e32 v156, s82, v195
	v_add_u32_e32 v183, s86, v195
	ds_read_b128 v[144:147], v156
	ds_read_b128 v[148:151], v156 offset:1024
	ds_read_b128 v[152:155], v156 offset:2048
	ds_read_b128 v[156:159], v156 offset:3072
	ds_read_b128 v[186:189], v183
	ds_read_b128 v[198:201], v183 offset:1024
	ds_read_b128 v[202:205], v183 offset:2048
	ds_read_b128 v[206:209], v183 offset:3072
	v_lshl_add_u64 v[242:243], s[38:39], 0, v[178:179]
	s_add_i32 m0, s63, 0xc000
	ds_read_b128 v[210:213], v197
	ds_read_b128 v[214:217], v197 offset:1024
	ds_read_b128 v[218:221], v197 offset:2048
	ds_read_b128 v[222:225], v197 offset:3072
	ds_read_b128 v[226:229], v197 offset:4096
	ds_read_b128 v[230:233], v197 offset:5120
	ds_read_b128 v[234:237], v197 offset:6144
	ds_read_b128 v[238:241], v197 offset:7168
	global_load_lds_dwordx4 v[242:243], off
	v_lshl_add_u64 v[242:243], s[38:39], 0, v[180:181]
	s_add_i32 m0, s63, 0xe000
	s_nop 0
	global_load_lds_dwordx4 v[242:243], off
	s_mov_b32 s100, 0
	s_cmp_eq_u32 s101, 0
	s_cbranch_scc1 .Lpka_w8a
	s_cmp_lt_i32 s81, 6
	s_cbranch_scc1 .Lpka_w8a
	s_mov_b32 s100, 1
	s_cmp_eq_u32 s101, 4
	s_cbranch_scc1 .Lpka_s0
	s_cmp_eq_u32 s101, 3
	s_cbranch_scc1 .Lpka_s1
	s_cmp_eq_u32 s101, 2
	s_cbranch_scc1 .Lpka_s2
	global_store_dwordx4 v[254:255], v[12:15], off offset:64
	s_branch .Lpka_w9a

; #define PG8_STAGE(bufoff, gbase, voff) do { _Pragma("unroll") for (int _i = 0; _i < 2; ++_i) \
;         __builtin_amdgcn_global_load_lds((const unsigned*)((const char*)(gbase) + (voff)[_i]), (PG8_LAS unsigned*)(lds + (bufoff) + ldsw + _i * 8192), 16, 0, 0); } while (0)
; #define PG8_LDA(dst, b, h) do { _Pragma("unroll") for (int m = 0; m < 4; ++m) _Pragma("unroll") for (int k = 0; k < 2; ++k) dst[m][k] = *(const PG8_LAS bf16x8*)(lds + PG8_SA(b, h) + aoff + m * 2048 + k * 1024); } while (0)
; #define PG8_WAIT_V(n) asm volatile("s_waitcnt vmcnt(" #n ")" ::: "memory")
; #define PG8_WAIT_L(n) asm volatile("s_waitcnt lgkmcnt(" #n ")" ::: "memory")
; #define PG8_BAR __builtin_amdgcn_s_barrier()
; #define PG8_SCHED __builtin_amdgcn_sched_barrier(0)
;     ...
;             PG8_WAIT_V(8); PG8_WAIT_L(0); PG8_BAR; PG8_MMA(0, 0, At, B0); PG8_MMA(0, 1, At, B1); PG8_BAR; PG8_SCHED;
;             PG8_LDA(At, 0, 1); PG8_STAGE(PG8_SB(0, 0), b2, voffB); PG8_STAGE(PG8_SB(0, 1), b2 + hstepB, voffB); PG8_STAGE(PG8_SA(0, 0), a2, voffA);
.Lpka_da:
	s_waitcnt lgkmcnt(0)
	s_barrier
	s_setprio 1
	s_waitcnt lgkmcnt(0)
	v_mfma_f32_16x16x32_bf16 v[132:135], v[144:147], v[210:213], v[132:135]
	v_mfma_f32_16x16x32_bf16 v[128:131], v[152:155], v[210:213], v[128:131]
	v_mfma_f32_16x16x32_bf16 v[116:119], v[144:147], v[218:221], v[116:119]
	v_mfma_f32_16x16x32_bf16 v[112:115], v[152:155], v[218:221], v[112:115]
	v_mfma_f32_16x16x32_bf16 v[100:103], v[144:147], v[226:229], v[100:103]
	v_mfma_f32_16x16x32_bf16 v[96:99], v[152:155], v[226:229], v[96:99]
	v_mfma_f32_16x16x32_bf16 v[84:87], v[144:147], v[234:237], v[84:87]
	v_mfma_f32_16x16x32_bf16 v[80:83], v[152:155], v[234:237], v[80:83]
	v_mfma_f32_16x16x32_bf16 v[132:135], v[148:151], v[214:217], v[132:135]
	v_mfma_f32_16x16x32_bf16 v[128:131], v[156:159], v[214:217], v[128:131]
	v_mfma_f32_16x16x32_bf16 v[116:119], v[148:151], v[222:225], v[116:119]
	v_mfma_f32_16x16x32_bf16 v[112:115], v[156:159], v[222:225], v[112:115]
	v_mfma_f32_16x16x32_bf16 v[100:103], v[148:151], v[230:233], v[100:103]
	v_mfma_f32_16x16x32_bf16 v[96:99], v[156:159], v[230:233], v[96:99]
	v_mfma_f32_16x16x32_bf16 v[84:87], v[148:151], v[238:241], v[84:87]
	v_mfma_f32_16x16x32_bf16 v[80:83], v[156:159], v[238:241], v[80:83]
	s_setprio 0
	s_setprio 1
	v_mfma_f32_16x16x32_bf16 v[140:143], v[186:189], v[210:213], v[140:143]
	v_mfma_f32_16x16x32_bf16 v[136:139], v[202:205], v[210:213], v[136:139]
	v_mfma_f32_16x16x32_bf16 v[124:127], v[186:189], v[218:221], v[124:127]
	v_mfma_f32_16x16x32_bf16 v[120:123], v[202:205], v[218:221], v[120:123]
	v_mfma_f32_16x16x32_bf16 v[108:111], v[186:189], v[226:229], v[108:111]
	v_mfma_f32_16x16x32_bf16 v[104:107], v[202:205], v[226:229], v[104:107]
	v_mfma_f32_16x16x32_bf16 v[92:95], v[186:189], v[234:237], v[92:95]
	v_mfma_f32_16x16x32_bf16 v[88:91], v[202:205], v[234:237], v[88:91]
	v_mfma_f32_16x16x32_bf16 v[140:143], v[198:201], v[214:217], v[140:143]
	v_mfma_f32_16x16x32_bf16 v[136:139], v[206:209], v[214:217], v[136:139]
	v_mfma_f32_16x16x32_bf16 v[124:127], v[198:201], v[222:225], v[124:127]
	v_mfma_f32_16x16x32_bf16 v[120:123], v[206:209], v[222:225], v[120:123]
	v_mfma_f32_16x16x32_bf16 v[108:111], v[198:201], v[230:233], v[108:111]
	v_mfma_f32_16x16x32_bf16 v[104:107], v[206:209], v[230:233], v[104:107]
	v_mfma_f32_16x16x32_bf16 v[92:95], v[198:201], v[238:241], v[92:95]
	v_mfma_f32_16x16x32_bf16 v[88:91], v[206:209], v[238:241], v[88:91]
	s_setprio 0
	s_barrier
	s_add_i32 s82, s82, s15
	v_lshl_add_u64 v[242:243], s[72:73], 0, v[170:171]
	s_mov_b32 m0, s82
	ds_read_b128 v[210:213], v197 offset:16384
	ds_read_b128 v[214:217], v197 offset:17408
	ds_read_b128 v[218:221], v197 offset:18432
	ds_read_b128 v[222:225], v197 offset:19456
	ds_read_b128 v[226:229], v197 offset:20480
	ds_read_b128 v[230:233], v197 offset:21504
	ds_read_b128 v[234:237], v197 offset:22528
	ds_read_b128 v[238:241], v197 offset:23552
	global_load_lds_dwordx4 v[242:243], off
	s_add_i32 m0, s82, 0x2000
	s_add_u32 s82, s72, 0x10000
	v_lshl_add_u64 v[244:245], s[72:73], 0, v[166:167]
	s_addc_u32 s83, s73, 0
	s_add_i32 s86, s86, s15
	global_load_lds_dwordx4 v[244:245], off
	v_lshl_add_u64 v[246:247], s[82:83], 0, v[170:171]
	s_mov_b32 m0, s86
	v_lshl_add_u64 v[248:249], s[76:77], 0, v[168:169]
	global_load_lds_dwordx4 v[246:247], off
	v_lshl_add_u64 v[246:247], s[82:83], 0, v[166:167]
	s_add_i32 m0, s86, 0x2000
	s_nop 0
	global_load_lds_dwordx4 v[246:247], off
	v_lshl_add_u64 v[246:247], s[76:77], 0, v[172:173]
	s_mov_b32 m0, s63
	s_nop 0
	global_load_lds_dwordx4 v[246:247], off
	s_mov_b32 m0, s64
	s_nop 0
	global_load_lds_dwordx4 v[248:249], off
	s_cmp_eq_u32 s100, 0
	s_cbranch_scc1 .Lpka_w8b
	s_waitcnt vmcnt(9)
	s_branch .Lpka_db

; #define PG8_STAGE(bufoff, gbase, voff) do { _Pragma("unroll") for (int _i = 0; _i < 2; ++_i) \
;         __builtin_amdgcn_global_load_lds((const unsigned*)((const char*)(gbase) + (voff)[_i]), (PG8_LAS unsigned*)(lds + (bufoff) + ldsw + _i * 8192), 16, 0, 0); } while (0)
; #define PG8_LDA(dst, b, h) do { _Pragma("unroll") for (int m = 0; m < 4; ++m) _Pragma("unroll") for (int k = 0; k < 2; ++k) dst[m][k] = *(const PG8_LAS bf16x8*)(lds + PG8_SA(b, h) + aoff + m * 2048 + k * 1024); } while (0)
; #define PG8_LDB(dst, b, h) do { _Pragma("unroll") for (int n = 0; n < 2; ++n) _Pragma("unroll") for (int k = 0; k < 2; ++k) dst[n][k] = *(const PG8_LAS bf16x8*)(lds + PG8_SB(b, h) + boff + n * 2048 + k * 1024); } while (0)
; #define PG8_WAIT_V(n) asm volatile("s_waitcnt vmcnt(" #n ")" ::: "memory")
; #define PG8_WAIT_L(n) asm volatile("s_waitcnt lgkmcnt(" #n ")" ::: "memory")
; #define PG8_BAR __builtin_amdgcn_s_barrier()
; #define PG8_SCHED __builtin_amdgcn_sched_barrier(0)
;     ...
;             PG8_WAIT_V(8); PG8_WAIT_L(0); PG8_BAR; PG8_MMA(1, 0, At, B0); PG8_MMA(1, 1, At, B1); PG8_BAR; PG8_SCHED;
;             PG8_LDB(B0, 1, 0); PG8_LDB(B1, 1, 1); PG8_SCHED; PG8_LDA(At, 1, 0); PG8_STAGE(PG8_SA(0, 1), a2 + hstep, voffA);
.Lpka_db:
	s_waitcnt lgkmcnt(0)
	s_barrier
	s_setprio 1
	s_waitcnt lgkmcnt(0)
	v_mfma_f32_16x16x32_bf16 v[68:71], v[144:147], v[210:213], v[68:71]
	v_mfma_f32_16x16x32_bf16 v[64:67], v[152:155], v[210:213], v[64:67]
	v_mfma_f32_16x16x32_bf16 v[52:55], v[144:147], v[218:221], v[52:55]
	v_mfma_f32_16x16x32_bf16 v[48:51], v[152:155], v[218:221], v[48:51]
	v_mfma_f32_16x16x32_bf16 v[36:39], v[144:147], v[226:229], v[36:39]
	v_mfma_f32_16x16x32_bf16 v[32:35], v[152:155], v[226:229], v[32:35]
	v_mfma_f32_16x16x32_bf16 v[20:23], v[144:147], v[234:237], v[20:23]
	v_mfma_f32_16x16x32_bf16 v[16:19], v[152:155], v[234:237], v[16:19]
	v_mfma_f32_16x16x32_bf16 v[68:71], v[148:151], v[214:217], v[68:71]
	v_mfma_f32_16x16x32_bf16 v[64:67], v[156:159], v[214:217], v[64:67]
	v_mfma_f32_16x16x32_bf16 v[52:55], v[148:151], v[222:225], v[52:55]
	v_mfma_f32_16x16x32_bf16 v[48:51], v[156:159], v[222:225], v[48:51]
	v_mfma_f32_16x16x32_bf16 v[36:39], v[148:151], v[230:233], v[36:39]
	v_mfma_f32_16x16x32_bf16 v[32:35], v[156:159], v[230:233], v[32:35]
	v_mfma_f32_16x16x32_bf16 v[20:23], v[148:151], v[238:241], v[20:23]
	v_mfma_f32_16x16x32_bf16 v[16:19], v[156:159], v[238:241], v[16:19]
	s_setprio 0
	s_setprio 1
	v_mfma_f32_16x16x32_bf16 v[76:79], v[186:189], v[210:213], v[76:79]
	v_mfma_f32_16x16x32_bf16 v[72:75], v[202:205], v[210:213], v[72:75]
	v_mfma_f32_16x16x32_bf16 v[60:63], v[186:189], v[218:221], v[60:63]
	v_mfma_f32_16x16x32_bf16 v[56:59], v[202:205], v[218:221], v[56:59]
	v_mfma_f32_16x16x32_bf16 v[44:47], v[186:189], v[226:229], v[44:47]
	v_mfma_f32_16x16x32_bf16 v[40:43], v[202:205], v[226:229], v[40:43]
	v_mfma_f32_16x16x32_bf16 v[24:27], v[186:189], v[234:237], v[24:27]
	v_mfma_f32_16x16x32_bf16 v[28:31], v[202:205], v[234:237], v[28:31]
	v_mfma_f32_16x16x32_bf16 v[76:79], v[198:201], v[214:217], v[76:79]
	v_mfma_f32_16x16x32_bf16 v[72:75], v[206:209], v[214:217], v[72:75]
	v_mfma_f32_16x16x32_bf16 v[60:63], v[198:201], v[222:225], v[60:63]
	v_mfma_f32_16x16x32_bf16 v[56:59], v[206:209], v[222:225], v[56:59]
	v_mfma_f32_16x16x32_bf16 v[44:47], v[198:201], v[230:233], v[44:47]
	v_mfma_f32_16x16x32_bf16 v[40:43], v[206:209], v[230:233], v[40:43]
	v_mfma_f32_16x16x32_bf16 v[24:27], v[198:201], v[238:241], v[24:27]
	v_mfma_f32_16x16x32_bf16 v[28:31], v[206:209], v[238:241], v[28:31]
	s_setprio 0
	s_barrier
	s_add_i32 s82, 0, 0x18000
	s_add_i32 s83, 0, 0x1c000
	v_add_u32_e32 v156, s82, v195
	v_add_u32_e32 v183, s83, v195
	ds_read_b128 v[144:147], v156
	ds_read_b128 v[148:151], v156 offset:1024
	ds_read_b128 v[152:155], v156 offset:2048
	ds_read_b128 v[156:159], v156 offset:3072
	ds_read_b128 v[186:189], v183
	ds_read_b128 v[198:201], v183 offset:1024
	ds_read_b128 v[202:205], v183 offset:2048
	ds_read_b128 v[206:209], v183 offset:3072
	s_add_u32 s76, s76, 0x40000
	s_addc_u32 s77, s77, 0
	s_mov_b32 m0, s65
	v_lshl_add_u64 v[250:251], s[76:77], 0, v[172:173]
	ds_read_b128 v[210:213], v197 offset:32768
	ds_read_b128 v[214:217], v197 offset:33792
	ds_read_b128 v[218:221], v197 offset:34816
	ds_read_b128 v[222:225], v197 offset:35840
	ds_read_b128 v[226:229], v197 offset:36864
	ds_read_b128 v[230:233], v197 offset:37888
	ds_read_b128 v[234:237], v197 offset:38912
	ds_read_b128 v[238:241], v197 offset:39936
	global_load_lds_dwordx4 v[250:251], off
	v_lshl_add_u64 v[250:251], s[76:77], 0, v[168:169]
	s_mov_b32 m0, s66
	s_nop 0
	global_load_lds_dwordx4 v[250:251], off
	s_cmp_eq_u32 s100, 0
	s_cbranch_scc1 .Lpka_w8c
	s_waitcnt vmcnt(9)
	s_branch .Lpka_dc

; #define PG8_STAGE(bufoff, gbase, voff) do { _Pragma("unroll") for (int _i = 0; _i < 2; ++_i) \
;         __builtin_amdgcn_global_load_lds((const unsigned*)((const char*)(gbase) + (voff)[_i]), (PG8_LAS unsigned*)(lds + (bufoff) + ldsw + _i * 8192), 16, 0, 0); } while (0)
; #define PG8_LDA(dst, b, h) do { _Pragma("unroll") for (int m = 0; m < 4; ++m) _Pragma("unroll") for (int k = 0; k < 2; ++k) dst[m][k] = *(const PG8_LAS bf16x8*)(lds + PG8_SA(b, h) + aoff + m * 2048 + k * 1024); } while (0)
; #define PG8_WAIT_V(n) asm volatile("s_waitcnt vmcnt(" #n ")" ::: "memory")
; #define PG8_WAIT_L(n) asm volatile("s_waitcnt lgkmcnt(" #n ")" ::: "memory")
; #define PG8_BAR __builtin_amdgcn_s_barrier()
; #define PG8_SCHED __builtin_amdgcn_sched_barrier(0)
;     ...
;             PG8_WAIT_V(8); PG8_WAIT_L(0); PG8_BAR; PG8_MMA(0, 0, At, B0); PG8_MMA(0, 1, At, B1); PG8_BAR; PG8_SCHED;
;             PG8_LDA(At, 1, 1); PG8_STAGE(PG8_SB(1, 0), b3, voffB); PG8_STAGE(PG8_SB(1, 1), b3 + hstepB, voffB); PG8_STAGE(PG8_SA(1, 0), a3, voffA);
;             PG8_WAIT_V(8); PG8_WAIT_L(0); PG8_BAR; PG8_MMA(1, 0, At, B0); PG8_MMA(1, 1, At, B1); PG8_BAR; PG8_SCHED;
;         }
.Lpka_dc:
	s_waitcnt lgkmcnt(0)
	s_barrier
	s_setprio 1
	s_waitcnt lgkmcnt(0)
	v_mfma_f32_16x16x32_bf16 v[132:135], v[144:147], v[210:213], v[132:135]
	v_mfma_f32_16x16x32_bf16 v[128:131], v[152:155], v[210:213], v[128:131]
	v_mfma_f32_16x16x32_bf16 v[116:119], v[144:147], v[218:221], v[116:119]
	v_mfma_f32_16x16x32_bf16 v[112:115], v[152:155], v[218:221], v[112:115]
	v_mfma_f32_16x16x32_bf16 v[100:103], v[144:147], v[226:229], v[100:103]
	v_mfma_f32_16x16x32_bf16 v[96:99], v[152:155], v[226:229], v[96:99]
	v_mfma_f32_16x16x32_bf16 v[84:87], v[144:147], v[234:237], v[84:87]
	v_mfma_f32_16x16x32_bf16 v[80:83], v[152:155], v[234:237], v[80:83]
	v_mfma_f32_16x16x32_bf16 v[132:135], v[148:151], v[214:217], v[132:135]
	v_mfma_f32_16x16x32_bf16 v[128:131], v[156:159], v[214:217], v[128:131]
	v_mfma_f32_16x16x32_bf16 v[116:119], v[148:151], v[222:225], v[116:119]
	v_mfma_f32_16x16x32_bf16 v[112:115], v[156:159], v[222:225], v[112:115]
	v_mfma_f32_16x16x32_bf16 v[100:103], v[148:151], v[230:233], v[100:103]
	v_mfma_f32_16x16x32_bf16 v[96:99], v[156:159], v[230:233], v[96:99]
	v_mfma_f32_16x16x32_bf16 v[84:87], v[148:151], v[238:241], v[84:87]
	v_mfma_f32_16x16x32_bf16 v[80:83], v[156:159], v[238:241], v[80:83]
	s_setprio 0
	s_setprio 1
	v_mfma_f32_16x16x32_bf16 v[140:143], v[186:189], v[210:213], v[140:143]
	v_mfma_f32_16x16x32_bf16 v[136:139], v[202:205], v[210:213], v[136:139]
	v_mfma_f32_16x16x32_bf16 v[124:127], v[186:189], v[218:221], v[124:127]
	v_mfma_f32_16x16x32_bf16 v[120:123], v[202:205], v[218:221], v[120:123]
	v_mfma_f32_16x16x32_bf16 v[108:111], v[186:189], v[226:229], v[108:111]
	v_mfma_f32_16x16x32_bf16 v[104:107], v[202:205], v[226:229], v[104:107]
	v_mfma_f32_16x16x32_bf16 v[92:95], v[186:189], v[234:237], v[92:95]
	v_mfma_f32_16x16x32_bf16 v[88:91], v[202:205], v[234:237], v[88:91]
	v_mfma_f32_16x16x32_bf16 v[140:143], v[198:201], v[214:217], v[140:143]
	v_mfma_f32_16x16x32_bf16 v[136:139], v[206:209], v[214:217], v[136:139]
	v_mfma_f32_16x16x32_bf16 v[124:127], v[198:201], v[222:225], v[124:127]
	v_mfma_f32_16x16x32_bf16 v[120:123], v[206:209], v[222:225], v[120:123]
	v_mfma_f32_16x16x32_bf16 v[108:111], v[198:201], v[230:233], v[108:111]
	v_mfma_f32_16x16x32_bf16 v[104:107], v[206:209], v[230:233], v[104:107]
	v_mfma_f32_16x16x32_bf16 v[92:95], v[198:201], v[238:241], v[92:95]
	v_mfma_f32_16x16x32_bf16 v[88:91], v[206:209], v[238:241], v[88:91]
	s_setprio 0
	s_barrier
	s_add_i32 s76, s82, s15
	v_lshl_add_u64 v[242:243], v[242:243], 0, s[4:5]
	s_mov_b32 m0, s76
	ds_read_b128 v[210:213], v197 offset:49152
	ds_read_b128 v[214:217], v197 offset:50176
	ds_read_b128 v[218:221], v197 offset:51200
	ds_read_b128 v[222:225], v197 offset:52224
	ds_read_b128 v[226:229], v197 offset:53248
	ds_read_b128 v[230:233], v197 offset:54272
	ds_read_b128 v[234:237], v197 offset:55296
	ds_read_b128 v[238:241], v197 offset:56320
	global_load_lds_dwordx4 v[242:243], off
	s_add_i32 m0, s76, 0x2000
	s_add_u32 s72, s72, 0x10080
	v_lshl_add_u64 v[242:243], v[244:245], 0, s[4:5]
	s_addc_u32 s73, s73, 0
	s_add_i32 s76, s83, s15
	global_load_lds_dwordx4 v[242:243], off
	v_lshl_add_u64 v[242:243], s[72:73], 0, v[170:171]
	s_mov_b32 m0, s76
	s_nop 0
	global_load_lds_dwordx4 v[242:243], off
	v_lshl_add_u64 v[242:243], s[72:73], 0, v[166:167]
	s_add_i32 m0, s76, 0x2000
	s_nop 0
	global_load_lds_dwordx4 v[242:243], off
	v_lshl_add_u64 v[242:243], v[246:247], 0, s[4:5]
	s_mov_b32 m0, s74
	s_nop 0
	global_load_lds_dwordx4 v[242:243], off
	v_lshl_add_u64 v[242:243], v[248:249], 0, s[4:5]
	s_mov_b32 m0, s75
	s_nop 0
	global_load_lds_dwordx4 v[242:243], off
	s_waitcnt vmcnt(8)
	s_waitcnt lgkmcnt(0)
	s_barrier
	s_setprio 1
	s_waitcnt lgkmcnt(0)
	v_mfma_f32_16x16x32_bf16 v[68:71], v[144:147], v[210:213], v[68:71]
	v_mfma_f32_16x16x32_bf16 v[64:67], v[152:155], v[210:213], v[64:67]
	v_mfma_f32_16x16x32_bf16 v[52:55], v[144:147], v[218:221], v[52:55]
	v_mfma_f32_16x16x32_bf16 v[48:51], v[152:155], v[218:221], v[48:51]
	v_mfma_f32_16x16x32_bf16 v[36:39], v[144:147], v[226:229], v[36:39]
	v_mfma_f32_16x16x32_bf16 v[32:35], v[152:155], v[226:229], v[32:35]
	v_mfma_f32_16x16x32_bf16 v[20:23], v[144:147], v[234:237], v[20:23]
	v_mfma_f32_16x16x32_bf16 v[16:19], v[152:155], v[234:237], v[16:19]
	v_mfma_f32_16x16x32_bf16 v[68:71], v[148:151], v[214:217], v[68:71]
	v_mfma_f32_16x16x32_bf16 v[64:67], v[156:159], v[214:217], v[64:67]
	v_mfma_f32_16x16x32_bf16 v[52:55], v[148:151], v[222:225], v[52:55]
	v_mfma_f32_16x16x32_bf16 v[48:51], v[156:159], v[222:225], v[48:51]
	v_mfma_f32_16x16x32_bf16 v[36:39], v[148:151], v[230:233], v[36:39]
	v_mfma_f32_16x16x32_bf16 v[32:35], v[156:159], v[230:233], v[32:35]
	v_mfma_f32_16x16x32_bf16 v[20:23], v[148:151], v[238:241], v[20:23]
	v_mfma_f32_16x16x32_bf16 v[16:19], v[156:159], v[238:241], v[16:19]
	s_setprio 0
	s_setprio 1
	v_mfma_f32_16x16x32_bf16 v[76:79], v[186:189], v[210:213], v[76:79]
	v_mfma_f32_16x16x32_bf16 v[72:75], v[202:205], v[210:213], v[72:75]
	v_mfma_f32_16x16x32_bf16 v[60:63], v[186:189], v[218:221], v[60:63]
	v_mfma_f32_16x16x32_bf16 v[56:59], v[202:205], v[218:221], v[56:59]
	v_mfma_f32_16x16x32_bf16 v[44:47], v[186:189], v[226:229], v[44:47]
	v_mfma_f32_16x16x32_bf16 v[40:43], v[202:205], v[226:229], v[40:43]
	v_mfma_f32_16x16x32_bf16 v[24:27], v[186:189], v[234:237], v[24:27]
	v_mfma_f32_16x16x32_bf16 v[28:31], v[202:205], v[234:237], v[28:31]
	v_mfma_f32_16x16x32_bf16 v[76:79], v[198:201], v[214:217], v[76:79]
	v_mfma_f32_16x16x32_bf16 v[72:75], v[206:209], v[214:217], v[72:75]
	v_mfma_f32_16x16x32_bf16 v[60:63], v[198:201], v[222:225], v[60:63]
	v_mfma_f32_16x16x32_bf16 v[56:59], v[206:209], v[222:225], v[56:59]
	v_mfma_f32_16x16x32_bf16 v[44:47], v[198:201], v[230:233], v[44:47]
	v_mfma_f32_16x16x32_bf16 v[40:43], v[206:209], v[230:233], v[40:43]
	v_mfma_f32_16x16x32_bf16 v[24:27], v[198:201], v[238:241], v[24:27]
	v_mfma_f32_16x16x32_bf16 v[28:31], v[206:209], v[238:241], v[28:31]
	s_setprio 0
	s_barrier
	s_sub_u32 s101, s101, s100
	s_add_i32 s81, s81, 2
	s_add_u32 s38, s38, 0x100
	s_addc_u32 s39, s39, 0
	s_add_u32 s61, s61, 0x100
	s_addc_u32 s80, s80, 0
	s_cmp_gt_u32 s81, 13
	s_cbranch_scc0 .LBB0_206
	s_and_b64 vcc, exec, s[22:23]
	s_cbranch_vccz .LBB0_209
	s_barrier
